# same as previous, DMA scalar temporaries renamed (s12:13) to free s100:101
# baseline (speedup 1.0000x reference)
; #define LAS __attribute__((address_space(3)))
; __device__ __forceinline__ void attn_unit(LAS unsigned char* lds, const bf16_t* __restrict__ U3, const bf16_t* __restrict__ VT, bf16_t* __restrict__ MIX, ...
;     ...
;         const bool mt = (t == NT - 1); const int k0 = mt ? 0 : NMETA + t * 64; LAS unsigned char* buf = lds + slot * STAGE; LAS unsigned char* pbuf = lds + slotp * STAGE;
;         const bool ahead = t + 2 < NT;
;         if (ahead) ATT_DMA(t + 2, slot2);
.LBB0_514:
	s_cmp_le_u32 s78, s75
	s_mov_b32 s81, s10
	s_cselect_b64 s[24:25], -1, 0
	s_lshl_b32 s12, s81, 15
	s_add_i32 s43, s12, 0
	v_add3_u32 v182, s43, v173, v171
	v_add3_u32 v183, s43, v174, v171
	v_add3_u32 v184, s43, v175, v171
	v_add3_u32 v185, s43, v176, v171
	ds_read_b128 v[96:99], v182
	ds_read_b128 v[186:189], v182 offset:8192
	ds_read_b128 v[190:193], v183
	ds_read_b128 v[194:197], v183 offset:8192
	ds_read_b128 v[198:201], v184
	ds_read_b128 v[218:221], v184 offset:8192
	ds_read_b128 v[222:225], v185
	ds_read_b128 v[226:229], v185 offset:8192
	s_cmp_gt_u32 s78, s75
	s_cbranch_scc1 .LBB0_516
	s_lshl_b32 s10, s45, 15
	s_add_i32 s14, s77, s10
	s_add_i32 s10, s84, s33
	s_cmp_lt_u32 s78, s75
	s_cselect_b32 s10, s10, 0x18000
	s_mul_i32 s11, s10, 0xc00
	s_add_i32 s11, s11, 0x400
	s_add_u32 s12, s20, s11
	s_addc_u32 s13, s21, 0
	s_mov_b32 m0, s14
	s_lshl_b32 s11, s10, 1
	global_load_lds_dwordx4 v146, s[12:13]
	s_add_i32 m0, s14, 0x2000
	s_nop 0
	global_load_lds_dwordx4 v150, s[12:13]
	s_add_u32 s12, s52, s11
	s_addc_u32 s13, s53, 0
	s_add_i32 m0, s14, 0x4000
	s_nop 0
	global_load_lds_dwordx4 v148, s[12:13]
	s_add_i32 m0, s14, 0x6000
	s_nop 0
	global_load_lds_dwordx4 v152, s[12:13]
